# sample-mLSTM unit: the three gate loads also requested at the top of the unit with the state rows
# baseline (speedup 1.0000x reference)
; DI void smlstm_unit(const Args& a, LAS unsigned char* lds, int s, int h) {
;     ...
;     if (tid < 128) { QF[tid] = bf2f(((const bf16_t*)(ws + WS_QB))[row * 512 + h * 128 + tid]); KF[tid] = bf2f(((const bf16_t*)(ws + WS_KB))[row * 512 + h * 128 + tid]); VF[tid] = bf2f(((const bf16_t*)(ws + WS_VB))[row * 512 + h * 128 + tid]); }
;     ...
;     const float* gr = (const float*)(ws + WS_GA) + row * 32; const float ip = gr[24 + h], fp = gr[28 + h], m0 = INF(a, I_SM)[sh];
;     const float lf = fminf(fp, 0.f) - log1pf(__expf(-fabsf(fp))), ain = lf + m0, mt = fmaxf(ain, ip), w_in = __expf(ain - mt), wi = __expf(ip - mt);
;     __syncthreads();
;     float num = 0.f; float* Co = a.out + O_CS + (size_t)sh * 16384; const float vv = VF[dv];
;     { float c0v[32];
; #pragma unroll
;       for (int i = 0; i < 32; ++i) c0v[i] = C0[(size_t)(part * 32 + i) * 128 + dv];
.LBB0_2126:
	s_add_i32 s0, s20, 0xfffffca0
	s_ashr_i32 s8, s0, 31
	s_lshr_b32 s8, s8, 25
	s_add_i32 s8, s0, s8
	s_and_b32 s8, s8, 0xffffff80
	s_sub_i32 s8, s0, s8
	s_ashr_i32 s0, s8, 2
	s_and_b32 s41, s8, 3
	s_addk_i32 s0, 0x4000
	s_ashr_i32 s101, s8, 31
	s_mov_b32 s100, s8
	s_lshl_b64 s[100:101], s[100:101], 16
	s_nop 0
	v_lshl_add_u64 v[214:215], v[134:135], 0, s[100:101]
	s_mov_b32 s101, 0
	s_mov_b32 s100, s38
	s_nop 0
	v_lshl_add_u64 v[216:217], v[214:215], 0, s[100:101]
	s_mov_b32 s100, s37
	s_nop 0
	v_lshl_add_u64 v[186:187], v[214:215], 0, s[100:101]
	s_mov_b32 s100, s22
	s_nop 0
	v_lshl_add_u64 v[188:189], v[214:215], 0, s[100:101]
	global_load_dword v219, v[214:215], off
	global_load_dword v220, v[214:215], off offset:512
	global_load_dword v221, v[214:215], off offset:1024
	global_load_dword v222, v[214:215], off offset:1536
	global_load_dword v223, v[214:215], off offset:2048
	global_load_dword v224, v[214:215], off offset:2560
	global_load_dword v225, v[214:215], off offset:3072
	global_load_dword v226, v[214:215], off offset:3584
	global_load_dword v227, v[216:217], off offset:-4096
	global_load_dword v190, v[186:187], off offset:512
	global_load_dword v191, v[186:187], off offset:1024
	global_load_dword v192, v[186:187], off offset:1536
	global_load_dword v193, v[216:217], off
	global_load_dword v194, v[216:217], off offset:512
	global_load_dword v195, v[216:217], off offset:1024
	global_load_dword v196, v[216:217], off offset:1536
	global_load_dword v197, v[216:217], off offset:2048
	global_load_dword v198, v[216:217], off offset:2560
	global_load_dword v199, v[216:217], off offset:3072
	global_load_dword v200, v[216:217], off offset:3584
	global_load_dword v201, v[186:187], off offset:2048
	global_load_dword v202, v[186:187], off offset:2560
	global_load_dword v203, v[186:187], off offset:3072
	global_load_dword v204, v[186:187], off offset:3584
	global_load_dword v205, v[188:189], off
	global_load_dword v206, v[188:189], off offset:512
	global_load_dword v207, v[188:189], off offset:1024
	global_load_dword v208, v[188:189], off offset:1536
	global_load_dword v209, v[188:189], off offset:2048
	global_load_dword v210, v[188:189], off offset:2560
	global_load_dword v211, v[188:189], off offset:3072
	global_load_dword v212, v[188:189], off offset:3584
	s_lshl_b64 s[100:101], s[0:1], 7
	s_add_u32 s100, s23, s100
	s_addc_u32 s101, s24, s101
	s_lshl_b32 s42, s41, 2
	v_mov_b32_e32 v228, s42
	global_load_dword v229, v228, s[100:101] offset:112
	global_load_dword v230, v228, s[100:101] offset:96
	s_ashr_i32 s43, s8, 31
	s_mov_b32 s42, s8
	s_lshl_b64 s[42:43], s[42:43], 2
	v_readlane_b32 s100, v253, 36
	v_readlane_b32 s101, v253, 37
	s_add_u32 s42, s100, s42
	s_addc_u32 s43, s101, s43
	global_load_dword v231, v133, s[42:43]
	s_barrier
	s_and_saveexec_b64 s[16:17], s[2:3]
	s_cbranch_execz .LBB0_2128
	s_lshl_b64 s[18:19], s[0:1], 9
	s_lshl_b32 s9, s41, 7
	s_or_b32 s9, s18, s9
	v_mov_b32_e32 v3, s19
	v_or_b32_e32 v2, s9, v0
	v_lshlrev_b64 v[2:3], 1, v[2:3]
	v_lshl_add_u64 v[4:5], s[10:11], 0, v[2:3]
	v_lshl_add_u64 v[6:7], s[12:13], 0, v[2:3]
	v_lshl_add_u64 v[2:3], s[14:15], 0, v[2:3]
	global_load_ushort v4, v[4:5], off
	s_nop 0
	global_load_ushort v5, v[6:7], off
	s_nop 0
	global_load_ushort v2, v[2:3], off
	s_waitcnt vmcnt(2)
	v_lshlrev_b32_e32 v3, 16, v4
	s_waitcnt vmcnt(1)
	v_lshlrev_b32_e32 v4, 16, v5
	s_waitcnt vmcnt(0)
	v_lshlrev_b32_e32 v2, 16, v2
	ds_write2st64_b32 v218, v3, v4 offset1:2
	ds_write_b32 v218, v2 offset:1024

; DI void smlstm_unit(const Args& a, LAS unsigned char* lds, int s, int h) {
;     ...
;     const float* gr = (const float*)(ws + WS_GA) + row * 32; const float ip = gr[24 + h], fp = gr[28 + h], m0 = INF(a, I_SM)[sh];
;     const float lf = fminf(fp, 0.f) - log1pf(__expf(-fabsf(fp))), ain = lf + m0, mt = fmaxf(ain, ip), w_in = __expf(ain - mt), wi = __expf(ip - mt);
.LBB0_2131:
	s_or_b64 exec, exec, s[20:21]
	s_ashr_i32 s9, s8, 31
	s_lshl_b64 s[20:21], s[0:1], 7
	s_add_u32 s20, s23, s20
	s_addc_u32 s21, s24, s21
	s_lshl_b32 s42, s41, 2
	v_mov_b32_e32 v2, s42
	s_waitcnt vmcnt(0)
	v_mov_b32_e32 v6, v229
	v_mov_b32_e32 v8, v230
	s_lshl_b64 s[20:21], s[8:9], 2
	v_readlane_b32 s44, v253, 36
	v_readlane_b32 s45, v253, 37
	s_add_u32 s20, s44, s20
	s_addc_u32 s21, s45, s21
	v_mov_b32_e32 v9, v231
	s_lshl_b64 s[42:43], s[8:9], 16
	v_lshl_add_u64 v[2:3], v[134:135], 0, s[42:43]
	s_waitcnt lgkmcnt(1)
	v_add_co_u32_e32 v4, vcc, s38, v2
	s_waitcnt lgkmcnt(0)
	s_nop 0
	v_addc_co_u32_e32 v5, vcc, 0, v3, vcc
	s_barrier
	s_waitcnt vmcnt(3)
	v_mov_b32_e32 v19, v219
	v_mov_b32_e32 v32, v220
	v_mov_b32_e32 v33, v221
	v_mov_b32_e32 v34, v222
	v_mov_b32_e32 v44, v223
	v_mov_b32_e32 v45, v224
	v_mov_b32_e32 v46, v225
	v_mov_b32_e32 v47, v226
	v_mov_b32_e32 v48, v227
	s_add_u32 s20, s25, s42
	s_addc_u32 s21, s26, s43
	v_readlane_b32 s46, v253, 38
	v_readlane_b32 s47, v253, 39
	v_readlane_b32 s48, v253, 40
	v_readlane_b32 s49, v253, 41
	v_readlane_b32 s50, v253, 42
	v_readlane_b32 s51, v253, 43
	v_readlane_b32 s52, v253, 44
	v_readlane_b32 s53, v253, 45
	v_readlane_b32 s54, v253, 46
	v_readlane_b32 s55, v253, 47
	v_readlane_b32 s56, v253, 48
	v_readlane_b32 s57, v253, 49
	v_readlane_b32 s58, v253, 50
	v_readlane_b32 s59, v253, 51
	s_waitcnt vmcnt(2)
	v_mul_f32_e64 v7, |v6|, s31
	v_exp_f32_e32 v10, v7
	v_max_f32_e32 v6, v6, v6
	v_min_f32_e32 v12, 0, v6
	s_waitcnt vmcnt(1)
	v_max_f32_e32 v11, v8, v8
	v_add_f32_e32 v13, 1.0, v10
	v_add_f32_e32 v14, -1.0, v13
	v_frexp_mant_f32_e32 v15, v13
	v_cvt_f64_f32_e32 v[6:7], v13
	v_sub_f32_e32 v16, v14, v13
	v_frexp_exp_i32_f64_e32 v6, v[6:7]
	v_cmp_gt_f32_e32 vcc, s33, v15
	v_sub_f32_e32 v14, v10, v14
	v_add_f32_e32 v7, 1.0, v16
	v_subbrev_co_u32_e32 v6, vcc, 0, v6, vcc
	v_add_f32_e32 v7, v14, v7
	v_sub_u32_e32 v14, 0, v6
	v_cvt_f32_i32_e32 v6, v6
	v_ldexp_f32 v13, v13, v14
	v_ldexp_f32 v7, v7, v14
	v_add_f32_e32 v14, -1.0, v13
	v_add_f32_e32 v15, 1.0, v13
	v_add_f32_e32 v16, 1.0, v14
	v_add_f32_e32 v17, -1.0, v15
	v_sub_f32_e32 v16, v13, v16
	v_sub_f32_e32 v13, v13, v17
	v_mul_f32_e32 v17, 0x3f317218, v6
	v_add_f32_e32 v16, v7, v16
	v_add_f32_e32 v7, v7, v13
	v_fma_f32 v13, v6, s34, -v17
	v_add_f32_e32 v18, v14, v16
	v_add_f32_e32 v20, v15, v7
	v_fmac_f32_e32 v13, 0xb102e308, v6
	v_sub_f32_e32 v6, v18, v14
	v_sub_f32_e32 v14, v20, v15
	v_rcp_f32_e32 v15, v20
	v_add_f32_e32 v21, v17, v13
	v_sub_f32_e32 v7, v7, v14
	v_sub_f32_e32 v14, v21, v17
	v_sub_f32_e32 v13, v13, v14
	v_mul_f32_e32 v14, v18, v15
	v_sub_f32_e32 v6, v16, v6
	v_mul_f32_e32 v16, v20, v14
	v_fma_f32 v17, v14, v20, -v16
	v_fmac_f32_e32 v17, v14, v7
	v_add_f32_e32 v22, v16, v17
	v_sub_f32_e32 v23, v18, v22
	v_sub_f32_e32 v16, v22, v16
	v_sub_f32_e32 v18, v18, v23
	v_sub_f32_e32 v16, v16, v17
	v_sub_f32_e32 v17, v18, v22
	v_add_f32_e32 v6, v6, v17
	v_add_f32_e32 v6, v16, v6
	v_add_f32_e32 v16, v23, v6
	v_mul_f32_e32 v17, v15, v16
	v_sub_f32_e32 v18, v23, v16
	v_mul_f32_e32 v22, v20, v17
	v_add_f32_e32 v6, v6, v18
	v_add_f32_e32 v18, v14, v17
	v_fma_f32 v20, v17, v20, -v22
	v_sub_f32_e32 v14, v18, v14
	v_fmac_f32_e32 v20, v17, v7
	v_sub_f32_e32 v7, v17, v14
	v_add_f32_e32 v14, v22, v20
	v_sub_f32_e32 v17, v14, v22
	v_sub_f32_e32 v22, v16, v14
	v_sub_f32_e32 v16, v16, v22
	v_sub_f32_e32 v14, v16, v14
	v_sub_f32_e32 v17, v17, v20
	v_add_f32_e32 v6, v6, v14
	v_add_f32_e32 v6, v17, v6
	v_add_f32_e32 v6, v22, v6
	v_mul_f32_e32 v6, v15, v6
	v_add_f32_e32 v6, v7, v6
	v_add_f32_e32 v7, v18, v6
	v_mul_f32_e32 v14, v7, v7
	v_fmamk_f32 v17, v14, 0x3e9b6dac, v138
	v_sub_f32_e32 v15, v7, v18
	v_ldexp_f32 v16, v7, 1
	v_mul_f32_e32 v7, v7, v14
	v_fmaak_f32 v14, v14, v17, 0x3f2aaada
	v_mul_f32_e32 v7, v7, v14
	v_add_f32_e32 v14, v16, v7
	v_sub_f32_e32 v6, v6, v15
	v_sub_f32_e32 v15, v14, v16
	v_ldexp_f32 v6, v6, 1
	v_sub_f32_e32 v7, v7, v15
	v_add_f32_e32 v6, v6, v7
	v_add_f32_e32 v7, v14, v6
	v_sub_f32_e32 v14, v7, v14
	v_add_f32_e32 v15, v21, v7
	v_sub_f32_e32 v6, v6, v14
	v_sub_f32_e32 v14, v15, v21
	v_sub_f32_e32 v16, v15, v14
	v_sub_f32_e32 v7, v7, v14
	v_add_f32_e32 v14, v13, v6
	v_sub_f32_e32 v16, v21, v16
	v_sub_f32_e32 v17, v14, v13
	v_add_f32_e32 v7, v7, v16
	v_sub_f32_e32 v16, v14, v17
	v_sub_f32_e32 v6, v6, v17
	v_sub_f32_e32 v13, v13, v16
	v_add_f32_e32 v7, v14, v7
	v_add_f32_e32 v6, v6, v13
	v_add_f32_e32 v13, v15, v7
	v_sub_f32_e32 v14, v13, v15
	v_sub_f32_e32 v7, v7, v14
	v_add_f32_e32 v6, v6, v7
	v_add_f32_e32 v6, v13, v6
	v_cmp_neq_f32_e32 vcc, s35, v10
	s_nop 1
	v_cndmask_b32_e32 v6, v181, v6, vcc
	v_cmp_ngt_f32_e32 vcc, -1.0, v10
	s_nop 1
	v_cndmask_b32_e32 v6, v182, v6, vcc
	v_cmp_neq_f32_e32 vcc, -1.0, v10
	s_nop 1
	v_cndmask_b32_e32 v6, v183, v6, vcc
	v_cmp_lt_f32_e64 vcc, |v10|, s36
	s_nop 1
	v_cndmask_b32_e32 v6, v6, v10, vcc
	v_sub_f32_e32 v6, v12, v6
	s_waitcnt vmcnt(0)
	v_add_f32_e32 v6, v9, v6
	v_max_f32_e32 v18, v6, v11
	v_sub_f32_e32 v6, v6, v18
	v_sub_f32_e32 v7, v8, v18
	v_mul_f32_e32 v28, 0x3fb8aa3b, v6
	v_add_co_u32_e32 v6, vcc, s37, v2
	v_mul_f32_e32 v29, 0x3fb8aa3b, v7
	s_nop 0
	v_addc_co_u32_e32 v7, vcc, 0, v3, vcc
	s_waitcnt vmcnt(0)
	v_mov_b32_e32 v49, v190
	v_mov_b32_e32 v50, v191
	v_mov_b32_e32 v51, v192
	v_mov_b32_e32 v52, v193
	v_mov_b32_e32 v53, v194
	v_mov_b32_e32 v54, v195
	v_mov_b32_e32 v55, v196
	v_mov_b32_e32 v16, v197
	v_mov_b32_e32 v17, v198
	v_mov_b32_e32 v14, v199
	v_mov_b32_e32 v15, v200
	v_add_co_u32_e32 v4, vcc, s22, v2
	s_nop 1
	v_addc_co_u32_e32 v5, vcc, 0, v3, vcc
	v_mov_b32_e32 v2, v201
	v_mov_b32_e32 v56, v202
	v_mov_b32_e32 v57, v203
	v_mov_b32_e32 v58, v204
	v_mov_b32_e32 v12, v205
	ds_read_b32 v3, v131 offset:1024
	ds_read_b128 v[20:23], v136
	v_mov_b32_e32 v13, v206
	v_mov_b32_e32 v10, v207
	v_mov_b32_e32 v11, v208
	v_mov_b32_e32 v8, v209
	v_mov_b32_e32 v9, v210
	v_mov_b32_e32 v6, v211
	v_mov_b32_e32 v7, v212
	ds_read_b128 v[24:27], v136 offset:512
	v_exp_f32_e32 v4, v29
	v_exp_f32_e32 v5, v28
	s_waitcnt vmcnt(31) lgkmcnt(1)
; DI void smlstm_unit(const Args& a, LAS unsigned char* lds, int s, int h) {
;     ...
;     float num = 0.f; float* Co = a.out + O_CS + (size_t)sh * 16384; const float vv = VF[dv];
;     { float c0v[32];
; #pragma unroll
;       for (int i = 0; i < 32; ++i) c0v[i] = C0[(size_t)(part * 32 + i) * 128 + dv];
; #pragma unroll
;       for (int i = 0; i < 32; ++i) { const int dk = part * 32 + i; num += QF[dk] * c0v[i]; Co[(size_t)dk * 128 + dv] = w_in * c0v[i] + wi * KF[dk] * vv; } }
;     RED[part * 128 + dv] = num;
;     __syncthreads();
	v_fma_f32 v59, v19, v20, 0
	s_waitcnt vmcnt(30)
	v_fmac_f32_e32 v59, v32, v21
	s_waitcnt lgkmcnt(0)
	v_mul_f32_e32 v20, v24, v4
	v_mul_f32_e32 v20, v3, v20
	v_fmac_f32_e32 v20, v19, v5
	v_mul_f32_e32 v19, v25, v4
	v_mul_f32_e32 v19, v3, v19
	v_fmac_f32_e32 v19, v32, v5
	global_store_dword v140, v19, s[20:21]
	v_mul_f32_e32 v19, v26, v4
	v_mul_f32_e32 v19, v3, v19
	s_waitcnt vmcnt(30)
	v_fmac_f32_e32 v19, v33, v5
	global_store_dword v141, v19, s[20:21]
	v_mul_f32_e32 v19, v27, v4
	v_mul_f32_e32 v19, v3, v19
	v_fmac_f32_e32 v59, v33, v22
	s_waitcnt vmcnt(30)
	v_fmac_f32_e32 v19, v34, v5
	ds_read_b128 v[28:31], v136 offset:112
	global_store_dword v139, v20, s[20:21]
	v_fmac_f32_e32 v59, v34, v23
	ds_read_b128 v[20:23], v136 offset:16
	global_store_dword v142, v19, s[20:21]
	ds_read_b128 v[24:27], v136 offset:528
	ds_read_b128 v[32:35], v136 offset:32
	ds_read_b128 v[36:39], v136 offset:48
	ds_read_b128 v[40:43], v136 offset:544
	s_waitcnt lgkmcnt(3)
	v_mul_f32_e32 v19, v24, v4
	s_waitcnt vmcnt(31)
	v_fmac_f32_e32 v59, v44, v20
	v_mul_f32_e32 v19, v3, v19
	v_fmac_f32_e32 v19, v44, v5
	s_waitcnt vmcnt(30)
	v_fmac_f32_e32 v59, v45, v21
	global_store_dword v143, v19, s[20:21]
	v_mul_f32_e32 v19, v25, v4
	s_waitcnt vmcnt(30)
	v_fmac_f32_e32 v59, v46, v22
	v_mul_f32_e32 v19, v3, v19
	s_waitcnt vmcnt(29)
	v_fmac_f32_e32 v59, v47, v23
	v_fmac_f32_e32 v19, v45, v5
	s_waitcnt vmcnt(28) lgkmcnt(2)
	v_fmac_f32_e32 v59, v48, v32
	global_store_dword v144, v19, s[20:21]
	v_mul_f32_e32 v19, v26, v4
	v_mul_f32_e32 v19, v3, v19
	v_fmac_f32_e32 v19, v46, v5
	global_store_dword v145, v19, s[20:21]
	v_mul_f32_e32 v19, v27, v4
	v_mul_f32_e32 v19, v3, v19
	v_fmac_f32_e32 v19, v47, v5
	global_store_dword v146, v19, s[20:21]
	ds_read_b128 v[20:23], v136 offset:560
	ds_read_b128 v[24:27], v136 offset:64
	s_waitcnt vmcnt(30)
	v_fmac_f32_e32 v59, v49, v33
	s_waitcnt vmcnt(29)
	v_fmac_f32_e32 v59, v50, v34
	s_waitcnt vmcnt(28)
	v_fmac_f32_e32 v59, v51, v35
	ds_read_b128 v[32:35], v136 offset:576
	s_waitcnt vmcnt(19) lgkmcnt(4)
	v_fmac_f32_e32 v59, v2, v36
	s_waitcnt vmcnt(18)
	v_fmac_f32_e32 v59, v56, v37
	s_waitcnt vmcnt(17)
	v_fmac_f32_e32 v59, v57, v38
	s_waitcnt vmcnt(16)
	v_fmac_f32_e32 v59, v58, v39
	ds_read_b128 v[36:39], v136 offset:96
	s_waitcnt lgkmcnt(4)
	v_mul_f32_e32 v19, v40, v4
	v_mul_f32_e32 v19, v3, v19
	v_fmac_f32_e32 v19, v48, v5
	global_store_dword v147, v19, s[20:21]
	v_mul_f32_e32 v19, v41, v4
	v_mul_f32_e32 v19, v3, v19
	v_fmac_f32_e32 v19, v49, v5
	global_store_dword v148, v19, s[20:21]
	v_mul_f32_e32 v19, v42, v4
	v_mul_f32_e32 v19, v3, v19
	v_fmac_f32_e32 v19, v50, v5
	global_store_dword v149, v19, s[20:21]
	v_mul_f32_e32 v19, v4, v43
	v_mul_f32_e32 v19, v3, v19
	v_fmac_f32_e32 v19, v51, v5
	global_store_dword v150, v19, s[20:21]
	s_waitcnt lgkmcnt(3)
	v_mul_f32_e32 v19, v4, v20
	v_mul_f32_e32 v19, v3, v19
	v_fmac_f32_e32 v19, v2, v5
	v_mul_f32_e32 v2, v4, v21
	v_mul_f32_e32 v2, v3, v2
	v_fmac_f32_e32 v2, v56, v5
	global_store_dword v152, v2, s[20:21]
	v_mul_f32_e32 v2, v4, v22
	v_mul_f32_e32 v2, v3, v2
	v_fmac_f32_e32 v2, v57, v5
	global_store_dword v153, v2, s[20:21]
	v_mul_f32_e32 v2, v4, v23
	v_mul_f32_e32 v2, v3, v2
	v_fmac_f32_e32 v2, v58, v5
	global_store_dword v154, v2, s[20:21]
	s_waitcnt lgkmcnt(1)
	v_mul_f32_e32 v2, v4, v32
	v_mul_f32_e32 v2, v3, v2
	v_fmac_f32_e32 v2, v52, v5
	global_store_dword v155, v2, s[20:21]
	v_mul_f32_e32 v2, v4, v33
	ds_read_b128 v[20:23], v136 offset:80
	v_fmac_f32_e32 v59, v52, v24
	v_mul_f32_e32 v2, v3, v2
	v_fmac_f32_e32 v59, v53, v25
	v_fmac_f32_e32 v2, v53, v5
	global_store_dword v156, v2, s[20:21]
	v_fmac_f32_e32 v59, v54, v26
	v_mul_f32_e32 v2, v4, v34
	v_mul_f32_e32 v2, v3, v2
	v_fmac_f32_e32 v59, v55, v27
	ds_read_b128 v[24:27], v136 offset:592
	v_fmac_f32_e32 v2, v54, v5
	global_store_dword v157, v2, s[20:21]
	v_mul_f32_e32 v2, v4, v35
	v_mul_f32_e32 v2, v3, v2
	v_fmac_f32_e32 v2, v55, v5
	global_store_dword v160, v2, s[20:21]
	ds_read_b128 v[32:35], v136 offset:608
	s_waitcnt lgkmcnt(1)
	v_mul_f32_e32 v2, v4, v24
	v_mul_f32_e32 v2, v3, v2
	v_fmac_f32_e32 v2, v16, v5
	v_pk_mul_f32 v[20:21], v[16:17], v[20:21]
	v_mul_f32_e32 v16, v4, v25
	v_mul_f32_e32 v16, v3, v16
	v_fmac_f32_e32 v16, v17, v5
	global_store_dword v162, v16, s[20:21]
	v_mul_f32_e32 v16, v4, v26
	v_mul_f32_e32 v16, v3, v16
	v_fmac_f32_e32 v16, v14, v5
	global_store_dword v163, v16, s[20:21]
	v_pk_mul_f32 v[16:17], v[14:15], v[22:23]
	v_mul_f32_e32 v14, v4, v27
	v_mul_f32_e32 v14, v3, v14
	v_fmac_f32_e32 v14, v15, v5
	global_store_dword v164, v14, s[20:21]
	s_waitcnt lgkmcnt(0)
	v_mul_f32_e32 v14, v4, v32
	v_mul_f32_e32 v14, v3, v14
	s_waitcnt vmcnt(29)
	v_fmac_f32_e32 v14, v12, v5
	global_store_dword v165, v14, s[20:21]
	s_waitcnt vmcnt(29)
	v_pk_mul_f32 v[14:15], v[12:13], v[36:37]
	v_mul_f32_e32 v12, v4, v33
	global_store_dword v161, v2, s[20:21]
	v_add_f32_e32 v2, v59, v20
	v_mul_f32_e32 v12, v3, v12
	v_add_f32_e32 v2, v2, v21
	v_fmac_f32_e32 v12, v13, v5
	v_add_f32_e32 v2, v2, v16
	global_store_dword v166, v12, s[20:21]
	v_mul_f32_e32 v12, v4, v34
	v_add_f32_e32 v2, v2, v17
	v_mul_f32_e32 v12, v3, v12
	v_add_f32_e32 v2, v2, v14
	s_waitcnt vmcnt(30)
	v_fmac_f32_e32 v12, v10, v5
	v_add_f32_e32 v2, v2, v15
	global_store_dword v167, v12, s[20:21]
	s_waitcnt vmcnt(30)
	v_pk_mul_f32 v[12:13], v[10:11], v[38:39]
	v_mul_f32_e32 v10, v4, v35
	v_add_f32_e32 v2, v2, v12
	v_add_f32_e32 v2, v2, v13
	ds_read_b128 v[12:15], v136 offset:624
	v_mul_f32_e32 v10, v3, v10
	v_fmac_f32_e32 v10, v11, v5
	global_store_dword v168, v10, s[20:21]
	global_store_dword v151, v19, s[20:21]
	s_waitcnt lgkmcnt(0)
	v_mul_f32_e32 v10, v4, v12
	v_mul_f32_e32 v10, v3, v10
	s_waitcnt vmcnt(31)
	v_fmac_f32_e32 v10, v8, v5
	global_store_dword v169, v10, s[20:21]
	s_waitcnt vmcnt(31)
	v_pk_mul_f32 v[10:11], v[8:9], v[28:29]
	v_mul_f32_e32 v8, v4, v13
	v_mul_f32_e32 v8, v3, v8
	v_fmac_f32_e32 v8, v9, v5
	global_store_dword v170, v8, s[20:21]
	v_mul_f32_e32 v8, v4, v14
	v_mul_f32_e32 v8, v3, v8
	v_add_f32_e32 v2, v2, v10
	s_waitcnt vmcnt(31)
	v_fmac_f32_e32 v8, v6, v5
	v_add_f32_e32 v2, v2, v11
	global_store_dword v171, v8, s[20:21]
	s_waitcnt vmcnt(31)
	v_pk_mul_f32 v[8:9], v[6:7], v[30:31]
	v_mul_f32_e32 v6, v4, v15
	v_add_f32_e32 v2, v2, v8
	v_mul_f32_e32 v6, v3, v6
	v_add_f32_e32 v2, v2, v9
	v_fmac_f32_e32 v6, v7, v5
	global_store_dword v172, v6, s[20:21]
	ds_write_b32 v218, v2 offset:1536
	s_waitcnt lgkmcnt(0)
	s_barrier
; DI void smlstm_unit(const Args& a, LAS unsigned char* lds, int s, int h) {
;     ...
;     if (tid < 128) { const float nt = (RED[dv] + RED[128 + dv]) + (RED[256 + dv] + RED[384 + dv]); const float sw = SCL[0] * wi; const float den = w_in * SCL[1] + sw;
;         HV[dv] = (w_in * nt + sw * vv) / fmaxf(fabsf(den), __expf(-mt));
;         a.out[O_NS + sh * 128 + dv] = w_in * n0[dv] + wi * KF[dv];
;         if (tid == 0) a.out[O_MS + sh] = mt; }
	s_and_saveexec_b64 s[20:21], s[2:3]
	s_cbranch_execz .LBB0_2134
	v_lshlrev_b32_e32 v132, 2, v130
	global_load_dword v6, v132, s[18:19]
	ds_read2st64_b32 v[8:9], v131 offset0:2 offset1:6
	ds_read2st64_b32 v[10:11], v218 offset0:8 offset1:10
	ds_read_b32 v13, v218 offset:3072
	ds_read_b64 v[14:15], v133 offset:4096
	v_mul_f32_e32 v7, 0xbfb8aa3b, v18
	s_waitcnt lgkmcnt(3)
	v_mov_b32_e32 v12, v9
	v_exp_f32_e32 v7, v7
	s_waitcnt lgkmcnt(1)
	v_pk_add_f32 v[10:11], v[10:11], v[12:13]
	v_mov_b32_e32 v2, v5
	v_mov_b32_e32 v16, v5
	v_mov_b32_e32 v17, v4
	s_waitcnt lgkmcnt(0)
	v_pk_mul_f32 v[4:5], v[4:5], v[14:15]
	v_pk_add_f32 v[10:11], v[10:11], v[10:11] op_sel:[0,1] op_sel_hi:[1,0]
	v_add_f32_e32 v5, v4, v5
	v_mov_b32_e32 v11, v4
	v_pk_mul_f32 v[2:3], v[2:3], v[10:11]
	v_max_f32_e64 v5, |v5|, v7
	v_add_f32_e32 v3, v2, v3
	v_div_scale_f32 v2, s[18:19], v5, v5, v3
	v_rcp_f32_e32 v4, v2
	v_mov_b32_e32 v7, v8
	v_div_scale_f32 v8, vcc, v3, v5, v3
	v_fma_f32 v9, -v2, v4, 1.0
	v_fmac_f32_e32 v4, v9, v4
	v_readlane_b32 s44, v253, 0
	v_mul_f32_e32 v9, v8, v4
	v_readlane_b32 s46, v253, 2
	v_fma_f32 v10, -v2, v9, v8
	v_readlane_b32 s47, v253, 3
	s_add_u32 s16, s46, s16
	v_fmac_f32_e32 v9, v10, v4
	s_addc_u32 s17, s47, s17
	v_fma_f32 v2, -v2, v9, v8
	v_lshl_add_u64 v[20:21], s[16:17], 0, v[132:133]
	v_div_fmas_f32 v4, v2, v4, v9
	v_add_co_u32_e32 v2, vcc, 0x7e34000, v20
	v_div_fixup_f32 v3, v4, v5, v3
	v_readlane_b32 s18, v254, 43
	ds_write_b32 v131, v3 offset:3584
	v_addc_co_u32_e32 v3, vcc, 0, v21, vcc
	v_readlane_b32 s19, v254, 44
	v_readlane_b32 s45, v253, 1
	s_waitcnt vmcnt(0)
	v_pk_mul_f32 v[4:5], v[16:17], v[6:7]
	s_nop 0
	v_add_f32_e32 v4, v4, v5
	global_store_dword v[2:3], v4, off offset:128
	s_and_b64 exec, exec, s[18:19]
	s_cbranch_execz .LBB0_2134
	s_mul_hi_i32 s9, s8, 0xfffffe04
	s_mulk_i32 s8, 0xfe04
	s_add_u32 s8, s16, s8
	s_addc_u32 s9, s17, s9
	global_store_dword v173, v18, s[8:9] offset:128
